# speedup vs baseline: 1.0005x; 1.0005x over previous
; __global__ void __launch_bounds__(512, 2) hymba_fwd(Params p) {
;     ...
;     if (C.G == 0x7fffffff) grid.sync();
.LBB0_227:
	s_sleep 3
	global_load_dword v2, v0, s[2:3] offset:32 sc1
	s_waitcnt vmcnt(0)
	v_and_b32_e32 v2, 0xffff0000, v2
	v_cmp_ne_u32_e32 vcc, v2, v1
	s_or_b64 s[4:5], vcc, s[4:5]
	s_andn2_b64 exec, exec, s[4:5]
	s_cbranch_execnz .LBB0_227

; __device__ __forceinline__ unsigned xb_ld(unsigned* p)              { return __hip_atomic_load(p, __ATOMIC_RELAXED, __HIP_MEMORY_SCOPE_AGENT); }
; __device__ __forceinline__ void xcd_barrier_complete(unsigned* bar, unsigned x, unsigned& nloc, unsigned& nx) {
;     ...
;     for (;;) {
;         sum = 0u; cnt = 0u; mine = 0u;
; #pragma unroll
;         for (unsigned j = 0; j < 16; ++j) { const unsigned c = xb_ld(&bar[XB_XCNT(j)]); sum += c; cnt += (c > 0u) ? 1u : 0u; mine = (j == x) ? c : mine; }
;         if (sum == G) break;
;         __builtin_amdgcn_s_sleep(1);
;         if ((++sp & 255u) == 0u) { if (xb_ld(&bar[XB_TMO])) break; if (sp > XB_SPIN_CAP) { atomicAdd(&bar[XB_TMO], 1u); break; } }
;     }
.LBB0_234:
	global_load_dword v15, v16, s[2:3] sc1
	s_waitcnt lgkmcnt(0)
	global_load_dword v0, v16, s[4:5] sc1
	global_load_dword v1, v16, s[8:9] sc1
	global_load_dword v2, v16, s[16:17] sc1
	global_load_dword v3, v16, s[22:23] sc1
	global_load_dword v4, v16, s[24:25] sc1
	global_load_dword v5, v16, s[26:27] sc1
	global_load_dword v6, v16, s[28:29] sc1
	global_load_dword v7, v16, s[30:31] sc1
	global_load_dword v8, v16, s[36:37] sc1
	global_load_dword v9, v16, s[38:39] sc1
	global_load_dword v10, v16, s[44:45] sc1
	global_load_dword v11, v16, s[48:49] sc1
	global_load_dword v12, v16, s[50:51] sc1
	global_load_dword v13, v16, s[52:53] sc1
	global_load_dword v14, v16, s[54:55] sc1
	s_mov_b64 s[60:61], -1
	s_mov_b64 s[62:63], -1
	s_waitcnt vmcnt(14)
	v_add_u32_e32 v17, v0, v15
	s_waitcnt vmcnt(13)
	v_add_u32_e32 v17, v17, v1
	s_waitcnt vmcnt(12)
	v_add_u32_e32 v17, v17, v2
	s_waitcnt vmcnt(11)
	v_add_u32_e32 v17, v17, v3
	s_waitcnt vmcnt(10)
	v_add_u32_e32 v17, v17, v4
	s_waitcnt vmcnt(9)
	v_add_u32_e32 v17, v17, v5
	s_waitcnt vmcnt(8)
	v_add_u32_e32 v17, v17, v6
	s_waitcnt vmcnt(7)
	v_add_u32_e32 v17, v17, v7
	s_waitcnt vmcnt(6)
	v_add_u32_e32 v17, v17, v8
	s_waitcnt vmcnt(5)
	v_add_u32_e32 v17, v17, v9
	s_waitcnt vmcnt(4)
	v_add_u32_e32 v17, v17, v10
	s_waitcnt vmcnt(3)
	v_add_u32_e32 v17, v17, v11
	s_waitcnt vmcnt(2)
	v_add_u32_e32 v17, v17, v12
	s_waitcnt vmcnt(1)
	v_add_u32_e32 v17, v17, v13
	s_waitcnt vmcnt(0)
	v_add_u32_e32 v17, v17, v14
	v_cmp_eq_u32_e32 vcc, s7, v17
	s_cbranch_vccnz .LBB0_233
	s_and_b32 s60, s35, 0xff
	s_cmp_eq_u32 s60, 0
	s_mov_b64 s[60:61], -1
	s_mov_b64 s[64:65], -1
	s_sleep 3
	s_cbranch_scc0 .LBB0_238
	global_load_dword v17, v16, s[46:47] sc1
	s_waitcnt vmcnt(0)
	v_cmp_eq_u32_e32 vcc, 0, v17
	s_cbranch_vccnz .LBB0_240
	s_mov_b64 s[64:65], 0

; __device__ __forceinline__ unsigned xb_ld(unsigned* p)              { return __hip_atomic_load(p, __ATOMIC_RELAXED, __HIP_MEMORY_SCOPE_AGENT); }
; __device__ __forceinline__ unsigned xb_add(unsigned* p, unsigned v) { return __hip_atomic_fetch_add(p, v, __ATOMIC_RELAXED, __HIP_MEMORY_SCOPE_AGENT); }
; #define XB_SPIN(cond, bar) do { unsigned _sp = 0; while (cond) { __builtin_amdgcn_s_sleep(1); \
;     if ((++_sp & 255u) == 0u) { if (xb_ld(&(bar)[XB_TMO])) break; if (_sp > XB_SPIN_CAP) { atomicAdd(&(bar)[XB_TMO], 1u); break; } } } } while (0)
; __device__ __forceinline__ void xcd_barrier(const XcdBarrier& b) {
;     ...
;             else XB_SPIN(xb_ld(&bar[XB_TOPGEN]) == tg, bar);
;             __builtin_amdgcn_fence(__ATOMIC_ACQUIRE, "agent");
;             xb_add(&bar[XB_XGEN(b.x)], 1u);
;             asm volatile("s_waitcnt vmcnt(0)" ::: "memory");
;             { unsigned inv_probe_; const unsigned* invp_ = bar + XB_TMO; asm volatile("global_load_dword %0, %1, off sc1\n\ts_waitcnt vmcnt(0)" : "=v"(inv_probe_) : "v"(invp_) : "memory"); }
;         } else {
;             XB_SPIN(xb_ld(&bar[XB_XGEN(b.x)]) == gen, bar);
.LBB0_252:
	s_and_b32 s28, s7, 0xff
	s_mov_b64 s[26:27], -1
	s_cmp_lg_u32 s28, 0
	s_mov_b64 s[30:31], -1
	s_sleep 3
	s_cbranch_scc1 .LBB0_255
	global_load_dword v2, v0, s[46:47] sc1
	s_waitcnt vmcnt(0)
	v_cmp_eq_u32_e32 vcc, 0, v2
	s_cbranch_vccnz .LBB0_257
	s_mov_b64 s[30:31], 0
	s_mov_b64 s[28:29], -1

; __device__ __forceinline__ unsigned xb_ld(unsigned* p)              { return __hip_atomic_load(p, __ATOMIC_RELAXED, __HIP_MEMORY_SCOPE_AGENT); }
; __device__ __forceinline__ unsigned xb_add(unsigned* p, unsigned v) { return __hip_atomic_fetch_add(p, v, __ATOMIC_RELAXED, __HIP_MEMORY_SCOPE_AGENT); }
; #define XB_SPIN(cond, bar) do { unsigned _sp = 0; while (cond) { __builtin_amdgcn_s_sleep(1); \
;     if ((++_sp & 255u) == 0u) { if (xb_ld(&(bar)[XB_TMO])) break; if (_sp > XB_SPIN_CAP) { atomicAdd(&(bar)[XB_TMO], 1u); break; } } } } while (0)
; __device__ __forceinline__ void xcd_barrier(const XcdBarrier& b) {
;     ...
;             else XB_SPIN(xb_ld(&bar[XB_TOPGEN]) == tg, bar);
;             __builtin_amdgcn_fence(__ATOMIC_ACQUIRE, "agent");
;             xb_add(&bar[XB_XGEN(b.x)], 1u);
;             asm volatile("s_waitcnt vmcnt(0)" ::: "memory");
;             { unsigned inv_probe_; const unsigned* invp_ = bar + XB_TMO; asm volatile("global_load_dword %0, %1, off sc1\n\ts_waitcnt vmcnt(0)" : "=v"(inv_probe_) : "v"(invp_) : "memory"); }
;         } else {
;             XB_SPIN(xb_ld(&bar[XB_XGEN(b.x)]) == gen, bar);
.LBB0_269:
	s_and_b32 s26, s7, 0xff
	s_cmp_lg_u32 s26, 0
	s_mov_b64 s[28:29], -1
	s_sleep 3
	s_cbranch_scc1 .LBB0_272
	global_load_dword v1, v0, s[46:47] sc1
	s_waitcnt vmcnt(0)
	v_cmp_eq_u32_e32 vcc, 0, v1
	s_cbranch_vccnz .LBB0_274
	s_mov_b64 s[28:29], 0
	s_mov_b64 s[26:27], -1

; __device__ __forceinline__ unsigned xb_ld(unsigned* p)              { return __hip_atomic_load(p, __ATOMIC_RELAXED, __HIP_MEMORY_SCOPE_AGENT); }
; __device__ __forceinline__ void xcd_barrier_complete(unsigned* bar, unsigned x, unsigned& nloc, unsigned& nx) {
;     ...
;     for (;;) {
;         sum = 0u; cnt = 0u; mine = 0u;
; #pragma unroll
;         for (unsigned j = 0; j < 16; ++j) { const unsigned c = xb_ld(&bar[XB_XCNT(j)]); sum += c; cnt += (c > 0u) ? 1u : 0u; mine = (j == x) ? c : mine; }
;         if (sum == G) break;
;         __builtin_amdgcn_s_sleep(1);
;         if ((++sp & 255u) == 0u) { if (xb_ld(&bar[XB_TMO])) break; if (sp > XB_SPIN_CAP) { atomicAdd(&bar[XB_TMO], 1u); break; } }
;     }
.LBB0_302:
	global_load_dword v15, v16, s[2:3] sc1
	s_waitcnt lgkmcnt(0)
	global_load_dword v0, v16, s[4:5] sc1
	global_load_dword v1, v16, s[8:9] sc1
	global_load_dword v2, v16, s[16:17] sc1
	global_load_dword v3, v16, s[22:23] sc1
	global_load_dword v4, v16, s[24:25] sc1
	global_load_dword v5, v16, s[26:27] sc1
	global_load_dword v6, v16, s[28:29] sc1
	global_load_dword v7, v16, s[30:31] sc1
	global_load_dword v8, v16, s[36:37] sc1
	global_load_dword v9, v16, s[38:39] sc1
	global_load_dword v10, v16, s[48:49] sc1
	global_load_dword v11, v16, s[50:51] sc1
	global_load_dword v12, v16, s[52:53] sc1
	global_load_dword v13, v16, s[54:55] sc1
	global_load_dword v14, v16, s[60:61] sc1
	s_mov_b64 s[62:63], -1
	s_mov_b64 s[64:65], -1
	s_waitcnt vmcnt(14)
	v_add_u32_e32 v17, v0, v15
	s_waitcnt vmcnt(13)
	v_add_u32_e32 v17, v17, v1
	s_waitcnt vmcnt(12)
	v_add_u32_e32 v17, v17, v2
	s_waitcnt vmcnt(11)
	v_add_u32_e32 v17, v17, v3
	s_waitcnt vmcnt(10)
	v_add_u32_e32 v17, v17, v4
	s_waitcnt vmcnt(9)
	v_add_u32_e32 v17, v17, v5
	s_waitcnt vmcnt(8)
	v_add_u32_e32 v17, v17, v6
	s_waitcnt vmcnt(7)
	v_add_u32_e32 v17, v17, v7
	s_waitcnt vmcnt(6)
	v_add_u32_e32 v17, v17, v8
	s_waitcnt vmcnt(5)
	v_add_u32_e32 v17, v17, v9
	s_waitcnt vmcnt(4)
	v_add_u32_e32 v17, v17, v10
	s_waitcnt vmcnt(3)
	v_add_u32_e32 v17, v17, v11
	s_waitcnt vmcnt(2)
	v_add_u32_e32 v17, v17, v12
	s_waitcnt vmcnt(1)
	v_add_u32_e32 v17, v17, v13
	s_waitcnt vmcnt(0)
	v_add_u32_e32 v17, v17, v14
	v_cmp_eq_u32_e32 vcc, s7, v17
	s_cbranch_vccnz .LBB0_301
	s_and_b32 s62, s35, 0xff
	s_cmp_eq_u32 s62, 0
	s_mov_b64 s[62:63], -1
	s_mov_b64 s[66:67], -1
	s_sleep 3
	s_cbranch_scc0 .LBB0_306
	global_load_dword v17, v16, s[46:47] sc1
	s_waitcnt vmcnt(0)
	v_cmp_eq_u32_e32 vcc, 0, v17
	s_cbranch_vccnz .LBB0_308
	s_mov_b64 s[66:67], 0

; __device__ __forceinline__ unsigned xb_ld(unsigned* p)              { return __hip_atomic_load(p, __ATOMIC_RELAXED, __HIP_MEMORY_SCOPE_AGENT); }
; __device__ __forceinline__ void xcd_barrier_complete(unsigned* bar, unsigned x, unsigned& nloc, unsigned& nx) {
;     ...
;     for (;;) {
;         sum = 0u; cnt = 0u; mine = 0u;
; #pragma unroll
;         for (unsigned j = 0; j < 16; ++j) { const unsigned c = xb_ld(&bar[XB_XCNT(j)]); sum += c; cnt += (c > 0u) ? 1u : 0u; mine = (j == x) ? c : mine; }
;         if (sum == G) break;
;         __builtin_amdgcn_s_sleep(1);
;         if ((++sp & 255u) == 0u) { if (xb_ld(&bar[XB_TMO])) break; if (sp > XB_SPIN_CAP) { atomicAdd(&bar[XB_TMO], 1u); break; } }
;     }
.LBB0_391:
	global_load_dword v15, v16, s[4:5] sc1
	s_waitcnt lgkmcnt(0)
	global_load_dword v0, v16, s[8:9] sc1
	global_load_dword v1, v16, s[16:17] sc1
	global_load_dword v2, v16, s[18:19] sc1
	global_load_dword v3, v16, s[20:21] sc1
	global_load_dword v4, v16, s[22:23] sc1
	global_load_dword v5, v16, s[24:25] sc1
	global_load_dword v6, v16, s[26:27] sc1
	global_load_dword v7, v16, s[28:29] sc1
	global_load_dword v8, v16, s[30:31] sc1
	global_load_dword v9, v16, s[36:37] sc1
	global_load_dword v10, v16, s[38:39] sc1
	global_load_dword v11, v16, s[48:49] sc1
	global_load_dword v12, v16, s[50:51] sc1
	global_load_dword v13, v16, s[52:53] sc1
	global_load_dword v14, v16, s[54:55] sc1
	s_mov_b64 s[60:61], -1
	s_mov_b64 s[62:63], -1
	s_waitcnt vmcnt(14)
	v_add_u32_e32 v17, v0, v15
	s_waitcnt vmcnt(13)
	v_add_u32_e32 v17, v17, v1
	s_waitcnt vmcnt(12)
	v_add_u32_e32 v17, v17, v2
	s_waitcnt vmcnt(11)
	v_add_u32_e32 v17, v17, v3
	s_waitcnt vmcnt(10)
	v_add_u32_e32 v17, v17, v4
	s_waitcnt vmcnt(9)
	v_add_u32_e32 v17, v17, v5
	s_waitcnt vmcnt(8)
	v_add_u32_e32 v17, v17, v6
	s_waitcnt vmcnt(7)
	v_add_u32_e32 v17, v17, v7
	s_waitcnt vmcnt(6)
	v_add_u32_e32 v17, v17, v8
	s_waitcnt vmcnt(5)
	v_add_u32_e32 v17, v17, v9
	s_waitcnt vmcnt(4)
	v_add_u32_e32 v17, v17, v10
	s_waitcnt vmcnt(3)
	v_add_u32_e32 v17, v17, v11
	s_waitcnt vmcnt(2)
	v_add_u32_e32 v17, v17, v12
	s_waitcnt vmcnt(1)
	v_add_u32_e32 v17, v17, v13
	s_waitcnt vmcnt(0)
	v_add_u32_e32 v17, v17, v14
	v_cmp_eq_u32_e32 vcc, s7, v17
	s_cbranch_vccnz .LBB0_390
	s_and_b32 s60, s35, 0xff
	s_cmp_eq_u32 s60, 0
	s_mov_b64 s[60:61], -1
	s_mov_b64 s[64:65], -1
	s_sleep 3
	s_cbranch_scc0 .LBB0_395
	global_load_dword v17, v16, s[46:47] sc1
	s_waitcnt vmcnt(0)
	v_cmp_eq_u32_e32 vcc, 0, v17
	s_cbranch_vccnz .LBB0_397
	s_mov_b64 s[64:65], 0

; __device__ __forceinline__ unsigned xb_ld(unsigned* p)              { return __hip_atomic_load(p, __ATOMIC_RELAXED, __HIP_MEMORY_SCOPE_AGENT); }
; __device__ __forceinline__ unsigned xb_add(unsigned* p, unsigned v) { return __hip_atomic_fetch_add(p, v, __ATOMIC_RELAXED, __HIP_MEMORY_SCOPE_AGENT); }
; #define XB_SPIN(cond, bar) do { unsigned _sp = 0; while (cond) { __builtin_amdgcn_s_sleep(1); \
;     if ((++_sp & 255u) == 0u) { if (xb_ld(&(bar)[XB_TMO])) break; if (_sp > XB_SPIN_CAP) { atomicAdd(&(bar)[XB_TMO], 1u); break; } } } } while (0)
; __device__ __forceinline__ void xcd_barrier(const XcdBarrier& b) {
;     ...
;             else XB_SPIN(xb_ld(&bar[XB_TOPGEN]) == tg, bar);
;             __builtin_amdgcn_fence(__ATOMIC_ACQUIRE, "agent");
;             xb_add(&bar[XB_XGEN(b.x)], 1u);
;             asm volatile("s_waitcnt vmcnt(0)" ::: "memory");
;             { unsigned inv_probe_; const unsigned* invp_ = bar + XB_TMO; asm volatile("global_load_dword %0, %1, off sc1\n\ts_waitcnt vmcnt(0)" : "=v"(inv_probe_) : "v"(invp_) : "memory"); }
;         } else {
;             XB_SPIN(xb_ld(&bar[XB_XGEN(b.x)]) == gen, bar);
.LBB0_409:
	s_and_b32 s26, s7, 0xff
	s_mov_b64 s[24:25], -1
	s_cmp_lg_u32 s26, 0
	s_mov_b64 s[28:29], -1
	s_sleep 3
	s_cbranch_scc1 .LBB0_412
	global_load_dword v2, v0, s[46:47] sc1
	s_waitcnt vmcnt(0)
	v_cmp_eq_u32_e32 vcc, 0, v2
	s_cbranch_vccnz .LBB0_414
	s_mov_b64 s[28:29], 0
	s_mov_b64 s[26:27], -1

; __device__ __forceinline__ unsigned xb_ld(unsigned* p)              { return __hip_atomic_load(p, __ATOMIC_RELAXED, __HIP_MEMORY_SCOPE_AGENT); }
; __device__ __forceinline__ unsigned xb_add(unsigned* p, unsigned v) { return __hip_atomic_fetch_add(p, v, __ATOMIC_RELAXED, __HIP_MEMORY_SCOPE_AGENT); }
; #define XB_SPIN(cond, bar) do { unsigned _sp = 0; while (cond) { __builtin_amdgcn_s_sleep(1); \
;     if ((++_sp & 255u) == 0u) { if (xb_ld(&(bar)[XB_TMO])) break; if (_sp > XB_SPIN_CAP) { atomicAdd(&(bar)[XB_TMO], 1u); break; } } } } while (0)
; __device__ __forceinline__ void xcd_barrier(const XcdBarrier& b) {
;     ...
;             else XB_SPIN(xb_ld(&bar[XB_TOPGEN]) == tg, bar);
;             __builtin_amdgcn_fence(__ATOMIC_ACQUIRE, "agent");
;             xb_add(&bar[XB_XGEN(b.x)], 1u);
;             asm volatile("s_waitcnt vmcnt(0)" ::: "memory");
;             { unsigned inv_probe_; const unsigned* invp_ = bar + XB_TMO; asm volatile("global_load_dword %0, %1, off sc1\n\ts_waitcnt vmcnt(0)" : "=v"(inv_probe_) : "v"(invp_) : "memory"); }
;         } else {
;             XB_SPIN(xb_ld(&bar[XB_XGEN(b.x)]) == gen, bar);
.LBB0_426:
	s_and_b32 s24, s7, 0xff
	s_cmp_lg_u32 s24, 0
	s_mov_b64 s[26:27], -1
	s_sleep 3
	s_cbranch_scc1 .LBB0_429
	global_load_dword v1, v0, s[46:47] sc1
	s_waitcnt vmcnt(0)
	v_cmp_eq_u32_e32 vcc, 0, v1
	s_cbranch_vccnz .LBB0_431
	s_mov_b64 s[26:27], 0
	s_mov_b64 s[24:25], -1

; __device__ __forceinline__ unsigned xb_ld(unsigned* p)              { return __hip_atomic_load(p, __ATOMIC_RELAXED, __HIP_MEMORY_SCOPE_AGENT); }
; __device__ __forceinline__ void xcd_barrier_complete(unsigned* bar, unsigned x, unsigned& nloc, unsigned& nx) {
;     ...
;     for (;;) {
;         sum = 0u; cnt = 0u; mine = 0u;
; #pragma unroll
;         for (unsigned j = 0; j < 16; ++j) { const unsigned c = xb_ld(&bar[XB_XCNT(j)]); sum += c; cnt += (c > 0u) ? 1u : 0u; mine = (j == x) ? c : mine; }
;         if (sum == G) break;
;         __builtin_amdgcn_s_sleep(1);
;         if ((++sp & 255u) == 0u) { if (xb_ld(&bar[XB_TMO])) break; if (sp > XB_SPIN_CAP) { atomicAdd(&bar[XB_TMO], 1u); break; } }
;     }
.LBB0_515:
	global_load_dword v15, v16, s[4:5] sc1
	s_waitcnt lgkmcnt(0)
	global_load_dword v0, v16, s[6:7] sc1
	global_load_dword v1, v16, s[8:9] sc1
	global_load_dword v2, v16, s[10:11] sc1
	global_load_dword v3, v16, s[12:13] sc1
	global_load_dword v4, v16, s[14:15] sc1
	global_load_dword v5, v16, s[16:17] sc1
	global_load_dword v6, v16, s[18:19] sc1
	global_load_dword v7, v16, s[20:21] sc1
	global_load_dword v8, v16, s[22:23] sc1
	global_load_dword v9, v16, s[24:25] sc1
	global_load_dword v10, v16, s[26:27] sc1
	global_load_dword v11, v16, s[28:29] sc1
	global_load_dword v12, v16, s[30:31] sc1
	global_load_dword v13, v16, s[34:35] sc1
	global_load_dword v14, v16, s[36:37] sc1
	s_mov_b64 s[38:39], -1
	s_mov_b64 s[48:49], -1
	s_waitcnt vmcnt(14)
	v_add_u32_e32 v17, v0, v15
	s_waitcnt vmcnt(13)
	v_add_u32_e32 v17, v17, v1
	s_waitcnt vmcnt(12)
	v_add_u32_e32 v17, v17, v2
	s_waitcnt vmcnt(11)
	v_add_u32_e32 v17, v17, v3
	s_waitcnt vmcnt(10)
	v_add_u32_e32 v17, v17, v4
	s_waitcnt vmcnt(9)
	v_add_u32_e32 v17, v17, v5
	s_waitcnt vmcnt(8)
	v_add_u32_e32 v17, v17, v6
	s_waitcnt vmcnt(7)
	v_add_u32_e32 v17, v17, v7
	s_waitcnt vmcnt(6)
	v_add_u32_e32 v17, v17, v8
	s_waitcnt vmcnt(5)
	v_add_u32_e32 v17, v17, v9
	s_waitcnt vmcnt(4)
	v_add_u32_e32 v17, v17, v10
	s_waitcnt vmcnt(3)
	v_add_u32_e32 v17, v17, v11
	s_waitcnt vmcnt(2)
	v_add_u32_e32 v17, v17, v12
	s_waitcnt vmcnt(1)
	v_add_u32_e32 v17, v17, v13
	s_waitcnt vmcnt(0)
	v_add_u32_e32 v17, v17, v14
	v_cmp_eq_u32_e32 vcc, s52, v17
	s_cbranch_vccnz .LBB0_514
	s_and_b32 s38, s53, 0xff
	s_cmp_eq_u32 s38, 0
	s_mov_b64 s[38:39], -1
	s_mov_b64 s[50:51], -1
	s_sleep 3
	s_cbranch_scc0 .LBB0_519
	global_load_dword v17, v16, s[46:47] sc1
	s_waitcnt vmcnt(0)
	v_cmp_eq_u32_e32 vcc, 0, v17
	s_cbranch_vccnz .LBB0_521
	s_mov_b64 s[50:51], 0

; __device__ __forceinline__ unsigned xb_ld(unsigned* p)              { return __hip_atomic_load(p, __ATOMIC_RELAXED, __HIP_MEMORY_SCOPE_AGENT); }
; __device__ __forceinline__ unsigned xb_add(unsigned* p, unsigned v) { return __hip_atomic_fetch_add(p, v, __ATOMIC_RELAXED, __HIP_MEMORY_SCOPE_AGENT); }
; #define XB_SPIN(cond, bar) do { unsigned _sp = 0; while (cond) { __builtin_amdgcn_s_sleep(1); \
;     if ((++_sp & 255u) == 0u) { if (xb_ld(&(bar)[XB_TMO])) break; if (_sp > XB_SPIN_CAP) { atomicAdd(&(bar)[XB_TMO], 1u); break; } } } } while (0)
; __device__ __forceinline__ void xcd_barrier(const XcdBarrier& b) {
;     ...
;             else XB_SPIN(xb_ld(&bar[XB_TOPGEN]) == tg, bar);
;             __builtin_amdgcn_fence(__ATOMIC_ACQUIRE, "agent");
;             xb_add(&bar[XB_XGEN(b.x)], 1u);
;             asm volatile("s_waitcnt vmcnt(0)" ::: "memory");
;             { unsigned inv_probe_; const unsigned* invp_ = bar + XB_TMO; asm volatile("global_load_dword %0, %1, off sc1\n\ts_waitcnt vmcnt(0)" : "=v"(inv_probe_) : "v"(invp_) : "memory"); }
;         } else {
;             XB_SPIN(xb_ld(&bar[XB_XGEN(b.x)]) == gen, bar);
.LBB0_533:
	s_and_b32 s18, s22, 0xff
	s_mov_b64 s[16:17], -1
	s_cmp_lg_u32 s18, 0
	s_mov_b64 s[20:21], -1
	s_sleep 3
	s_cbranch_scc1 .LBB0_536
	global_load_dword v2, v0, s[46:47] sc1
	s_waitcnt vmcnt(0)
	v_cmp_eq_u32_e32 vcc, 0, v2
	s_cbranch_vccnz .LBB0_538
	s_mov_b64 s[20:21], 0
	s_mov_b64 s[18:19], -1

; __device__ __forceinline__ unsigned xb_ld(unsigned* p)              { return __hip_atomic_load(p, __ATOMIC_RELAXED, __HIP_MEMORY_SCOPE_AGENT); }
; __device__ __forceinline__ unsigned xb_add(unsigned* p, unsigned v) { return __hip_atomic_fetch_add(p, v, __ATOMIC_RELAXED, __HIP_MEMORY_SCOPE_AGENT); }
; #define XB_SPIN(cond, bar) do { unsigned _sp = 0; while (cond) { __builtin_amdgcn_s_sleep(1); \
;     if ((++_sp & 255u) == 0u) { if (xb_ld(&(bar)[XB_TMO])) break; if (_sp > XB_SPIN_CAP) { atomicAdd(&(bar)[XB_TMO], 1u); break; } } } } while (0)
; __device__ __forceinline__ void xcd_barrier(const XcdBarrier& b) {
;     ...
;             else XB_SPIN(xb_ld(&bar[XB_TOPGEN]) == tg, bar);
;             __builtin_amdgcn_fence(__ATOMIC_ACQUIRE, "agent");
;             xb_add(&bar[XB_XGEN(b.x)], 1u);
;             asm volatile("s_waitcnt vmcnt(0)" ::: "memory");
;             { unsigned inv_probe_; const unsigned* invp_ = bar + XB_TMO; asm volatile("global_load_dword %0, %1, off sc1\n\ts_waitcnt vmcnt(0)" : "=v"(inv_probe_) : "v"(invp_) : "memory"); }
;         } else {
;             XB_SPIN(xb_ld(&bar[XB_XGEN(b.x)]) == gen, bar);
.LBB0_550:
	s_and_b32 s16, s22, 0xff
	s_cmp_lg_u32 s16, 0
	s_mov_b64 s[18:19], -1
	s_sleep 3
	s_cbranch_scc1 .LBB0_553
	global_load_dword v1, v0, s[46:47] sc1
	s_waitcnt vmcnt(0)
	v_cmp_eq_u32_e32 vcc, 0, v1
	s_cbranch_vccnz .LBB0_555
	s_mov_b64 s[18:19], 0
	s_mov_b64 s[16:17], -1

; __device__ __forceinline__ unsigned xb_ld(unsigned* p)              { return __hip_atomic_load(p, __ATOMIC_RELAXED, __HIP_MEMORY_SCOPE_AGENT); }
; __device__ __forceinline__ void xcd_barrier_complete(unsigned* bar, unsigned x, unsigned& nloc, unsigned& nx) {
;     ...
;     for (;;) {
;         sum = 0u; cnt = 0u; mine = 0u;
; #pragma unroll
;         for (unsigned j = 0; j < 16; ++j) { const unsigned c = xb_ld(&bar[XB_XCNT(j)]); sum += c; cnt += (c > 0u) ? 1u : 0u; mine = (j == x) ? c : mine; }
;         if (sum == G) break;
;         __builtin_amdgcn_s_sleep(1);
;         if ((++sp & 255u) == 0u) { if (xb_ld(&bar[XB_TMO])) break; if (sp > XB_SPIN_CAP) { atomicAdd(&bar[XB_TMO], 1u); break; } }
;     }
.LBB0_601:
	global_load_dword v15, v16, s[6:7] sc1
	s_waitcnt lgkmcnt(0)
	global_load_dword v0, v16, s[8:9] sc1
	global_load_dword v1, v16, s[10:11] sc1
	global_load_dword v2, v16, s[12:13] sc1
	global_load_dword v3, v16, s[18:19] sc1
	global_load_dword v4, v16, s[20:21] sc1
	global_load_dword v5, v16, s[22:23] sc1
	global_load_dword v6, v16, s[24:25] sc1
	global_load_dword v7, v16, s[26:27] sc1
	global_load_dword v8, v16, s[28:29] sc1
	global_load_dword v9, v16, s[30:31] sc1
	global_load_dword v10, v16, s[34:35] sc1
	global_load_dword v11, v16, s[36:37] sc1
	global_load_dword v12, v16, s[38:39] sc1
	global_load_dword v13, v16, s[48:49] sc1
	global_load_dword v14, v16, s[50:51] sc1
	s_mov_b64 s[52:53], -1
	s_mov_b64 s[54:55], -1
	s_waitcnt vmcnt(14)
	v_add_u32_e32 v17, v0, v15
	s_waitcnt vmcnt(13)
	v_add_u32_e32 v17, v17, v1
	s_waitcnt vmcnt(12)
	v_add_u32_e32 v17, v17, v2
	s_waitcnt vmcnt(11)
	v_add_u32_e32 v17, v17, v3
	s_waitcnt vmcnt(10)
	v_add_u32_e32 v17, v17, v4
	s_waitcnt vmcnt(9)
	v_add_u32_e32 v17, v17, v5
	s_waitcnt vmcnt(8)
	v_add_u32_e32 v17, v17, v6
	s_waitcnt vmcnt(7)
	v_add_u32_e32 v17, v17, v7
	s_waitcnt vmcnt(6)
	v_add_u32_e32 v17, v17, v8
	s_waitcnt vmcnt(5)
	v_add_u32_e32 v17, v17, v9
	s_waitcnt vmcnt(4)
	v_add_u32_e32 v17, v17, v10
	s_waitcnt vmcnt(3)
	v_add_u32_e32 v17, v17, v11
	s_waitcnt vmcnt(2)
	v_add_u32_e32 v17, v17, v12
	s_waitcnt vmcnt(1)
	v_add_u32_e32 v17, v17, v13
	s_waitcnt vmcnt(0)
	v_add_u32_e32 v17, v17, v14
	v_cmp_eq_u32_e32 vcc, s60, v17
	s_cbranch_vccnz .LBB0_600
	s_and_b32 s52, s61, 0xff
	s_cmp_eq_u32 s52, 0
	s_mov_b64 s[52:53], -1
	s_mov_b64 s[58:59], -1
	s_sleep 3
	s_cbranch_scc0 .LBB0_605
	global_load_dword v17, v16, s[46:47] sc1
	s_waitcnt vmcnt(0)
	v_cmp_eq_u32_e32 vcc, 0, v17
	s_cbranch_vccnz .LBB0_607
	s_mov_b64 s[58:59], 0

; __device__ __forceinline__ unsigned xb_ld(unsigned* p)              { return __hip_atomic_load(p, __ATOMIC_RELAXED, __HIP_MEMORY_SCOPE_AGENT); }
; __device__ __forceinline__ unsigned xb_add(unsigned* p, unsigned v) { return __hip_atomic_fetch_add(p, v, __ATOMIC_RELAXED, __HIP_MEMORY_SCOPE_AGENT); }
; #define XB_SPIN(cond, bar) do { unsigned _sp = 0; while (cond) { __builtin_amdgcn_s_sleep(1); \
;     if ((++_sp & 255u) == 0u) { if (xb_ld(&(bar)[XB_TMO])) break; if (_sp > XB_SPIN_CAP) { atomicAdd(&(bar)[XB_TMO], 1u); break; } } } } while (0)
; __device__ __forceinline__ void xcd_barrier(const XcdBarrier& b) {
;     ...
;             else XB_SPIN(xb_ld(&bar[XB_TOPGEN]) == tg, bar);
;             __builtin_amdgcn_fence(__ATOMIC_ACQUIRE, "agent");
;             xb_add(&bar[XB_XGEN(b.x)], 1u);
;             asm volatile("s_waitcnt vmcnt(0)" ::: "memory");
;             { unsigned inv_probe_; const unsigned* invp_ = bar + XB_TMO; asm volatile("global_load_dword %0, %1, off sc1\n\ts_waitcnt vmcnt(0)" : "=v"(inv_probe_) : "v"(invp_) : "memory"); }
;         } else {
;             XB_SPIN(xb_ld(&bar[XB_XGEN(b.x)]) == gen, bar);
.LBB0_619:
	s_and_b32 s24, s28, 0xff
	s_mov_b64 s[22:23], -1
	s_cmp_lg_u32 s24, 0
	s_mov_b64 s[26:27], -1
	s_sleep 3
	s_cbranch_scc1 .LBB0_622
	global_load_dword v2, v0, s[46:47] sc1
	s_waitcnt vmcnt(0)
	v_cmp_eq_u32_e32 vcc, 0, v2
	s_cbranch_vccnz .LBB0_624
	s_mov_b64 s[26:27], 0
	s_mov_b64 s[24:25], -1

; __device__ __forceinline__ unsigned xb_ld(unsigned* p)              { return __hip_atomic_load(p, __ATOMIC_RELAXED, __HIP_MEMORY_SCOPE_AGENT); }
; __device__ __forceinline__ unsigned xb_add(unsigned* p, unsigned v) { return __hip_atomic_fetch_add(p, v, __ATOMIC_RELAXED, __HIP_MEMORY_SCOPE_AGENT); }
; #define XB_SPIN(cond, bar) do { unsigned _sp = 0; while (cond) { __builtin_amdgcn_s_sleep(1); \
;     if ((++_sp & 255u) == 0u) { if (xb_ld(&(bar)[XB_TMO])) break; if (_sp > XB_SPIN_CAP) { atomicAdd(&(bar)[XB_TMO], 1u); break; } } } } while (0)
; __device__ __forceinline__ void xcd_barrier(const XcdBarrier& b) {
;     ...
;             else XB_SPIN(xb_ld(&bar[XB_TOPGEN]) == tg, bar);
;             __builtin_amdgcn_fence(__ATOMIC_ACQUIRE, "agent");
;             xb_add(&bar[XB_XGEN(b.x)], 1u);
;             asm volatile("s_waitcnt vmcnt(0)" ::: "memory");
;             { unsigned inv_probe_; const unsigned* invp_ = bar + XB_TMO; asm volatile("global_load_dword %0, %1, off sc1\n\ts_waitcnt vmcnt(0)" : "=v"(inv_probe_) : "v"(invp_) : "memory"); }
;         } else {
;             XB_SPIN(xb_ld(&bar[XB_XGEN(b.x)]) == gen, bar);
.LBB0_636:
	s_and_b32 s22, s28, 0xff
	s_cmp_lg_u32 s22, 0
	s_mov_b64 s[24:25], -1
	s_sleep 3
	s_cbranch_scc1 .LBB0_639
	global_load_dword v1, v0, s[46:47] sc1
	s_waitcnt vmcnt(0)
	v_cmp_eq_u32_e32 vcc, 0, v1
	s_cbranch_vccnz .LBB0_641
	s_mov_b64 s[24:25], 0
	s_mov_b64 s[22:23], -1

; __device__ __forceinline__ unsigned xb_ld(unsigned* p)              { return __hip_atomic_load(p, __ATOMIC_RELAXED, __HIP_MEMORY_SCOPE_AGENT); }
; __device__ __forceinline__ void xcd_barrier_complete(unsigned* bar, unsigned x, unsigned& nloc, unsigned& nx) {
;     ...
;     for (;;) {
;         sum = 0u; cnt = 0u; mine = 0u;
; #pragma unroll
;         for (unsigned j = 0; j < 16; ++j) { const unsigned c = xb_ld(&bar[XB_XCNT(j)]); sum += c; cnt += (c > 0u) ? 1u : 0u; mine = (j == x) ? c : mine; }
;         if (sum == G) break;
;         __builtin_amdgcn_s_sleep(1);
;         if ((++sp & 255u) == 0u) { if (xb_ld(&bar[XB_TMO])) break; if (sp > XB_SPIN_CAP) { atomicAdd(&bar[XB_TMO], 1u); break; } }
;     }
.LBB0_697:
	global_load_dword v15, v16, s[6:7] sc1
	s_waitcnt lgkmcnt(0)
	global_load_dword v0, v16, s[8:9] sc1
	global_load_dword v1, v16, s[10:11] sc1
	global_load_dword v2, v16, s[12:13] sc1
	global_load_dword v3, v16, s[16:17] sc1
	global_load_dword v4, v16, s[20:21] sc1
	global_load_dword v5, v16, s[22:23] sc1
	global_load_dword v6, v16, s[24:25] sc1
	global_load_dword v7, v16, s[26:27] sc1
	global_load_dword v8, v16, s[28:29] sc1
	global_load_dword v9, v16, s[30:31] sc1
	global_load_dword v10, v16, s[34:35] sc1
	global_load_dword v11, v16, s[36:37] sc1
	global_load_dword v12, v16, s[38:39] sc1
	global_load_dword v13, v16, s[48:49] sc1
	global_load_dword v14, v16, s[50:51] sc1
	s_mov_b64 s[52:53], -1
	s_mov_b64 s[54:55], -1
	s_waitcnt vmcnt(14)
	v_add_u32_e32 v17, v0, v15
	s_waitcnt vmcnt(13)
	v_add_u32_e32 v17, v17, v1
	s_waitcnt vmcnt(12)
	v_add_u32_e32 v17, v17, v2
	s_waitcnt vmcnt(11)
	v_add_u32_e32 v17, v17, v3
	s_waitcnt vmcnt(10)
	v_add_u32_e32 v17, v17, v4
	s_waitcnt vmcnt(9)
	v_add_u32_e32 v17, v17, v5
	s_waitcnt vmcnt(8)
	v_add_u32_e32 v17, v17, v6
	s_waitcnt vmcnt(7)
	v_add_u32_e32 v17, v17, v7
	s_waitcnt vmcnt(6)
	v_add_u32_e32 v17, v17, v8
	s_waitcnt vmcnt(5)
	v_add_u32_e32 v17, v17, v9
	s_waitcnt vmcnt(4)
	v_add_u32_e32 v17, v17, v10
	s_waitcnt vmcnt(3)
	v_add_u32_e32 v17, v17, v11
	s_waitcnt vmcnt(2)
	v_add_u32_e32 v17, v17, v12
	s_waitcnt vmcnt(1)
	v_add_u32_e32 v17, v17, v13
	s_waitcnt vmcnt(0)
	v_add_u32_e32 v17, v17, v14
	v_cmp_eq_u32_e32 vcc, s60, v17
	s_cbranch_vccnz .LBB0_696
	s_and_b32 s52, s61, 0xff
	s_cmp_eq_u32 s52, 0
	s_mov_b64 s[52:53], -1
	s_mov_b64 s[58:59], -1
	s_sleep 3
	s_cbranch_scc0 .LBB0_701
	global_load_dword v17, v16, s[46:47] sc1
	s_waitcnt vmcnt(0)
	v_cmp_eq_u32_e32 vcc, 0, v17
	s_cbranch_vccnz .LBB0_703
	s_mov_b64 s[58:59], 0

; __device__ __forceinline__ unsigned xb_ld(unsigned* p)              { return __hip_atomic_load(p, __ATOMIC_RELAXED, __HIP_MEMORY_SCOPE_AGENT); }
; __device__ __forceinline__ void xcd_barrier_complete(unsigned* bar, unsigned x, unsigned& nloc, unsigned& nx) {
;     ...
;     for (;;) {
;         sum = 0u; cnt = 0u; mine = 0u;
; #pragma unroll
;         for (unsigned j = 0; j < 16; ++j) { const unsigned c = xb_ld(&bar[XB_XCNT(j)]); sum += c; cnt += (c > 0u) ? 1u : 0u; mine = (j == x) ? c : mine; }
;         if (sum == G) break;
;         __builtin_amdgcn_s_sleep(1);
;         if ((++sp & 255u) == 0u) { if (xb_ld(&bar[XB_TMO])) break; if (sp > XB_SPIN_CAP) { atomicAdd(&bar[XB_TMO], 1u); break; } }
;     }
.LBB0_765:
	global_load_dword v15, v16, s[4:5] sc1
	s_waitcnt lgkmcnt(0)
	global_load_dword v0, v16, s[6:7] sc1
	global_load_dword v1, v16, s[8:9] sc1
	global_load_dword v2, v16, s[10:11] sc1
	global_load_dword v3, v16, s[12:13] sc1
	global_load_dword v4, v16, s[16:17] sc1
	global_load_dword v5, v16, s[18:19] sc1
	global_load_dword v6, v16, s[20:21] sc1
	global_load_dword v7, v16, s[22:23] sc1
	global_load_dword v8, v16, s[24:25] sc1
	global_load_dword v9, v16, s[26:27] sc1
	global_load_dword v10, v16, s[28:29] sc1
	global_load_dword v11, v16, s[30:31] sc1
	global_load_dword v12, v16, s[34:35] sc1
	global_load_dword v13, v16, s[36:37] sc1
	global_load_dword v14, v16, s[38:39] sc1
	s_mov_b64 s[48:49], -1
	s_mov_b64 s[50:51], -1
	s_waitcnt vmcnt(14)
	v_add_u32_e32 v17, v0, v15
	s_waitcnt vmcnt(13)
	v_add_u32_e32 v17, v17, v1
	s_waitcnt vmcnt(12)
	v_add_u32_e32 v17, v17, v2
	s_waitcnt vmcnt(11)
	v_add_u32_e32 v17, v17, v3
	s_waitcnt vmcnt(10)
	v_add_u32_e32 v17, v17, v4
	s_waitcnt vmcnt(9)
	v_add_u32_e32 v17, v17, v5
	s_waitcnt vmcnt(8)
	v_add_u32_e32 v17, v17, v6
	s_waitcnt vmcnt(7)
	v_add_u32_e32 v17, v17, v7
	s_waitcnt vmcnt(6)
	v_add_u32_e32 v17, v17, v8
	s_waitcnt vmcnt(5)
	v_add_u32_e32 v17, v17, v9
	s_waitcnt vmcnt(4)
	v_add_u32_e32 v17, v17, v10
	s_waitcnt vmcnt(3)
	v_add_u32_e32 v17, v17, v11
	s_waitcnt vmcnt(2)
	v_add_u32_e32 v17, v17, v12
	s_waitcnt vmcnt(1)
	v_add_u32_e32 v17, v17, v13
	s_waitcnt vmcnt(0)
	v_add_u32_e32 v17, v17, v14
	v_cmp_eq_u32_e32 vcc, s54, v17
	s_cbranch_vccnz .LBB0_764
	s_and_b32 s48, s55, 0xff
	s_cmp_eq_u32 s48, 0
	s_mov_b64 s[48:49], -1
	s_mov_b64 s[52:53], -1
	s_sleep 3
	s_cbranch_scc0 .LBB0_769
	global_load_dword v17, v16, s[46:47] sc1
	s_waitcnt vmcnt(0)
	v_cmp_eq_u32_e32 vcc, 0, v17
	s_cbranch_vccnz .LBB0_771
	s_mov_b64 s[52:53], 0

; __device__ __forceinline__ unsigned xb_ld(unsigned* p)              { return __hip_atomic_load(p, __ATOMIC_RELAXED, __HIP_MEMORY_SCOPE_AGENT); }
; __device__ __forceinline__ unsigned xb_add(unsigned* p, unsigned v) { return __hip_atomic_fetch_add(p, v, __ATOMIC_RELAXED, __HIP_MEMORY_SCOPE_AGENT); }
; #define XB_SPIN(cond, bar) do { unsigned _sp = 0; while (cond) { __builtin_amdgcn_s_sleep(1); \
;     if ((++_sp & 255u) == 0u) { if (xb_ld(&(bar)[XB_TMO])) break; if (_sp > XB_SPIN_CAP) { atomicAdd(&(bar)[XB_TMO], 1u); break; } } } } while (0)
; __device__ __forceinline__ void xcd_barrier(const XcdBarrier& b) {
;     ...
;             else XB_SPIN(xb_ld(&bar[XB_TOPGEN]) == tg, bar);
;             __builtin_amdgcn_fence(__ATOMIC_ACQUIRE, "agent");
;             xb_add(&bar[XB_XGEN(b.x)], 1u);
;             asm volatile("s_waitcnt vmcnt(0)" ::: "memory");
;             { unsigned inv_probe_; const unsigned* invp_ = bar + XB_TMO; asm volatile("global_load_dword %0, %1, off sc1\n\ts_waitcnt vmcnt(0)" : "=v"(inv_probe_) : "v"(invp_) : "memory"); }
;         } else {
;             XB_SPIN(xb_ld(&bar[XB_XGEN(b.x)]) == gen, bar);
.LBB0_783:
	s_and_b32 s20, s24, 0xff
	s_mov_b64 s[18:19], -1
	s_cmp_lg_u32 s20, 0
	s_mov_b64 s[22:23], -1
	s_sleep 3
	s_cbranch_scc1 .LBB0_786
	global_load_dword v2, v0, s[46:47] sc1
	s_waitcnt vmcnt(0)
	v_cmp_eq_u32_e32 vcc, 0, v2
	s_cbranch_vccnz .LBB0_788
	s_mov_b64 s[22:23], 0
	s_mov_b64 s[20:21], -1

; __device__ __forceinline__ unsigned xb_ld(unsigned* p)              { return __hip_atomic_load(p, __ATOMIC_RELAXED, __HIP_MEMORY_SCOPE_AGENT); }
; __device__ __forceinline__ unsigned xb_add(unsigned* p, unsigned v) { return __hip_atomic_fetch_add(p, v, __ATOMIC_RELAXED, __HIP_MEMORY_SCOPE_AGENT); }
; #define XB_SPIN(cond, bar) do { unsigned _sp = 0; while (cond) { __builtin_amdgcn_s_sleep(1); \
;     if ((++_sp & 255u) == 0u) { if (xb_ld(&(bar)[XB_TMO])) break; if (_sp > XB_SPIN_CAP) { atomicAdd(&(bar)[XB_TMO], 1u); break; } } } } while (0)
; __device__ __forceinline__ void xcd_barrier(const XcdBarrier& b) {
;     ...
;             else XB_SPIN(xb_ld(&bar[XB_TOPGEN]) == tg, bar);
;             __builtin_amdgcn_fence(__ATOMIC_ACQUIRE, "agent");
;             xb_add(&bar[XB_XGEN(b.x)], 1u);
;             asm volatile("s_waitcnt vmcnt(0)" ::: "memory");
;             { unsigned inv_probe_; const unsigned* invp_ = bar + XB_TMO; asm volatile("global_load_dword %0, %1, off sc1\n\ts_waitcnt vmcnt(0)" : "=v"(inv_probe_) : "v"(invp_) : "memory"); }
;         } else {
;             XB_SPIN(xb_ld(&bar[XB_XGEN(b.x)]) == gen, bar);
.LBB0_800:
	s_and_b32 s18, s24, 0xff
	s_cmp_lg_u32 s18, 0
	s_mov_b64 s[20:21], -1
	s_sleep 3
	s_cbranch_scc1 .LBB0_803
	global_load_dword v1, v0, s[46:47] sc1
	s_waitcnt vmcnt(0)
	v_cmp_eq_u32_e32 vcc, 0, v1
	s_cbranch_vccnz .LBB0_805
	s_mov_b64 s[20:21], 0
	s_mov_b64 s[18:19], -1

; __device__ __forceinline__ unsigned xb_ld(unsigned* p)              { return __hip_atomic_load(p, __ATOMIC_RELAXED, __HIP_MEMORY_SCOPE_AGENT); }
; __device__ __forceinline__ void xcd_barrier_complete(unsigned* bar, unsigned x, unsigned& nloc, unsigned& nx) {
;     ...
;     for (;;) {
;         sum = 0u; cnt = 0u; mine = 0u;
; #pragma unroll
;         for (unsigned j = 0; j < 16; ++j) { const unsigned c = xb_ld(&bar[XB_XCNT(j)]); sum += c; cnt += (c > 0u) ? 1u : 0u; mine = (j == x) ? c : mine; }
;         if (sum == G) break;
;         __builtin_amdgcn_s_sleep(1);
;         if ((++sp & 255u) == 0u) { if (xb_ld(&bar[XB_TMO])) break; if (sp > XB_SPIN_CAP) { atomicAdd(&bar[XB_TMO], 1u); break; } }
;     }
.LBB0_910:
	global_load_dword v15, v16, s[4:5] sc1
	s_waitcnt lgkmcnt(0)
	global_load_dword v0, v16, s[6:7] sc1
	global_load_dword v1, v16, s[8:9] sc1
	global_load_dword v2, v16, s[10:11] sc1
	global_load_dword v3, v16, s[14:15] sc1
	global_load_dword v4, v16, s[16:17] sc1
	global_load_dword v5, v16, s[18:19] sc1
	global_load_dword v6, v16, s[20:21] sc1
	global_load_dword v7, v16, s[22:23] sc1
	global_load_dword v8, v16, s[24:25] sc1
	global_load_dword v9, v16, s[26:27] sc1
	global_load_dword v10, v16, s[28:29] sc1
	global_load_dword v11, v16, s[30:31] sc1
	global_load_dword v12, v16, s[34:35] sc1
	global_load_dword v13, v16, s[36:37] sc1
	global_load_dword v14, v16, s[38:39] sc1
	s_mov_b64 s[48:49], -1
	s_mov_b64 s[50:51], -1
	s_waitcnt vmcnt(14)
	v_add_u32_e32 v17, v0, v15
	s_waitcnt vmcnt(13)
	v_add_u32_e32 v17, v17, v1
	s_waitcnt vmcnt(12)
	v_add_u32_e32 v17, v17, v2
	s_waitcnt vmcnt(11)
	v_add_u32_e32 v17, v17, v3
	s_waitcnt vmcnt(10)
	v_add_u32_e32 v17, v17, v4
	s_waitcnt vmcnt(9)
	v_add_u32_e32 v17, v17, v5
	s_waitcnt vmcnt(8)
	v_add_u32_e32 v17, v17, v6
	s_waitcnt vmcnt(7)
	v_add_u32_e32 v17, v17, v7
	s_waitcnt vmcnt(6)
	v_add_u32_e32 v17, v17, v8
	s_waitcnt vmcnt(5)
	v_add_u32_e32 v17, v17, v9
	s_waitcnt vmcnt(4)
	v_add_u32_e32 v17, v17, v10
	s_waitcnt vmcnt(3)
	v_add_u32_e32 v17, v17, v11
	s_waitcnt vmcnt(2)
	v_add_u32_e32 v17, v17, v12
	s_waitcnt vmcnt(1)
	v_add_u32_e32 v17, v17, v13
	s_waitcnt vmcnt(0)
	v_add_u32_e32 v17, v17, v14
	v_cmp_eq_u32_e32 vcc, s54, v17
	s_cbranch_vccnz .LBB0_909
	s_and_b32 s48, s55, 0xff
	s_cmp_eq_u32 s48, 0
	s_mov_b64 s[48:49], -1
	s_mov_b64 s[52:53], -1
	s_sleep 3
	s_cbranch_scc0 .LBB0_914
	global_load_dword v17, v16, s[46:47] sc1
	s_waitcnt vmcnt(0)
	v_cmp_eq_u32_e32 vcc, 0, v17
	s_cbranch_vccnz .LBB0_916
	s_mov_b64 s[52:53], 0

; __device__ __forceinline__ unsigned xb_ld(unsigned* p)              { return __hip_atomic_load(p, __ATOMIC_RELAXED, __HIP_MEMORY_SCOPE_AGENT); }
; __device__ __forceinline__ void xcd_barrier_complete(unsigned* bar, unsigned x, unsigned& nloc, unsigned& nx) {
;     ...
;     for (;;) {
;         sum = 0u; cnt = 0u; mine = 0u;
; #pragma unroll
;         for (unsigned j = 0; j < 16; ++j) { const unsigned c = xb_ld(&bar[XB_XCNT(j)]); sum += c; cnt += (c > 0u) ? 1u : 0u; mine = (j == x) ? c : mine; }
;         if (sum == G) break;
;         __builtin_amdgcn_s_sleep(1);
;         if ((++sp & 255u) == 0u) { if (xb_ld(&bar[XB_TMO])) break; if (sp > XB_SPIN_CAP) { atomicAdd(&bar[XB_TMO], 1u); break; } }
;     }
.LBB0_978:
	global_load_dword v15, v16, s[4:5] sc1
	s_waitcnt lgkmcnt(0)
	global_load_dword v0, v16, s[6:7] sc1
	global_load_dword v1, v16, s[8:9] sc1
	global_load_dword v2, v16, s[10:11] sc1
	global_load_dword v3, v16, s[12:13] sc1
	global_load_dword v4, v16, s[14:15] sc1
	global_load_dword v5, v16, s[16:17] sc1
	global_load_dword v6, v16, s[18:19] sc1
	global_load_dword v7, v16, s[20:21] sc1
	global_load_dword v8, v16, s[22:23] sc1
	global_load_dword v9, v16, s[24:25] sc1
	global_load_dword v10, v16, s[26:27] sc1
	global_load_dword v11, v16, s[28:29] sc1
	global_load_dword v12, v16, s[30:31] sc1
	global_load_dword v13, v16, s[34:35] sc1
	global_load_dword v14, v16, s[36:37] sc1
	s_mov_b64 s[38:39], -1
	s_mov_b64 s[40:41], -1
	s_waitcnt vmcnt(14)
	v_add_u32_e32 v17, v0, v15
	s_waitcnt vmcnt(13)
	v_add_u32_e32 v17, v17, v1
	s_waitcnt vmcnt(12)
	v_add_u32_e32 v17, v17, v2
	s_waitcnt vmcnt(11)
	v_add_u32_e32 v17, v17, v3
	s_waitcnt vmcnt(10)
	v_add_u32_e32 v17, v17, v4
	s_waitcnt vmcnt(9)
	v_add_u32_e32 v17, v17, v5
	s_waitcnt vmcnt(8)
	v_add_u32_e32 v17, v17, v6
	s_waitcnt vmcnt(7)
	v_add_u32_e32 v17, v17, v7
	s_waitcnt vmcnt(6)
	v_add_u32_e32 v17, v17, v8
	s_waitcnt vmcnt(5)
	v_add_u32_e32 v17, v17, v9
	s_waitcnt vmcnt(4)
	v_add_u32_e32 v17, v17, v10
	s_waitcnt vmcnt(3)
	v_add_u32_e32 v17, v17, v11
	s_waitcnt vmcnt(2)
	v_add_u32_e32 v17, v17, v12
	s_waitcnt vmcnt(1)
	v_add_u32_e32 v17, v17, v13
	s_waitcnt vmcnt(0)
	v_add_u32_e32 v17, v17, v14
	v_cmp_eq_u32_e32 vcc, s43, v17
	s_cbranch_vccnz .LBB0_977
	s_and_b32 s38, s50, 0xff
	s_cmp_eq_u32 s38, 0
	s_mov_b64 s[38:39], -1
	s_mov_b64 s[48:49], -1
	s_sleep 3
	s_cbranch_scc0 .LBB0_982
	global_load_dword v17, v16, s[46:47] sc1
	s_waitcnt vmcnt(0)
	v_cmp_eq_u32_e32 vcc, 0, v17
	s_cbranch_vccnz .LBB0_984
	s_mov_b64 s[48:49], 0
